# prompt-MLA loop: static s_setprio 1 for the younger half (waves 4-7), on top of phase-E load batching
# baseline (speedup 1.0000x reference)
.LBB0_1055:
	s_sub_i32 s1, s12, 32
	s_lshr_b32 s1, s1, 1
	s_sub_i32 s9, 31, s1
	v_lshlrev_b32_e32 v1, 3, v165
	s_lshl_b32 s13, s9, 8
	s_lshl_b32 s17, s9, 2
	v_and_b32_e32 v5, 24, v1
	v_and_b32_e32 v2, 0xc0, v2
	v_readlane_b32 s9, v253, 19
	v_and_b32_e32 v173, 31, v164
	v_and_b32_e32 v4, 32, v4
	v_add3_u32 v2, s9, v5, v2
	s_add_i32 s46, s13, s81
	v_and_b32_e32 v1, 0x100, v1
	v_add3_u32 v174, v2, v4, v1
	v_or_b32_e32 v4, s46, v173
	v_ashrrev_i32_e32 v5, 31, v4
	v_readlane_b32 s18, v254, 7
	v_readlane_b32 s13, v254, 34
	v_lshlrev_b64 v[4:5], 4, v[4:5]
	v_readlane_b32 s19, v254, 8
	s_add_i32 s9, s17, 4
	s_add_i32 s13, s17, s13
	v_or_b32_e32 v1, s16, v4
	v_mov_b64_e32 v[6:7], s[18:19]
	s_movk_i32 s17, 0x180
	v_lshrrev_b32_e32 v172, 5, v165
	v_mad_u64_u32 v[6:7], s[18:19], v1, s17, v[6:7]
	v_mad_i32_i24 v7, v5, s17, v7
	v_lshlrev_b32_e32 v2, 4, v172
	v_lshl_add_u64 v[4:5], v[6:7], 0, v[2:3]
	global_load_dwordx4 v[114:117], v[4:5], off
	global_load_dwordx4 v[118:121], v[4:5], off offset:32
	global_load_dwordx4 v[122:125], v[4:5], off offset:64
	global_load_dwordx4 v[126:129], v[4:5], off offset:96
	global_load_dwordx4 v[130:133], v[4:5], off offset:128
	global_load_dwordx4 v[134:137], v[4:5], off offset:160
	global_load_dwordx4 v[138:141], v[4:5], off offset:192
	global_load_dwordx4 v[142:145], v[4:5], off offset:224
	global_load_dwordx4 v[146:149], v[4:5], off offset:256
	global_load_dwordx4 v[150:153], v[4:5], off offset:288
	global_load_dwordx4 v[154:157], v[4:5], off offset:320
	global_load_dwordx4 v[158:161], v[4:5], off offset:352
	v_lshlrev_b32_e32 v1, 4, v164
	s_movk_i32 s17, 0x70
	v_and_b32_e32 v4, 0x70, v1
	v_bitop3_b32 v175, v2, v1, s17 bitop3:0x78
	s_movk_i32 s17, 0x60
	v_bitop3_b32 v178, v2, v4, s17 bitop3:0x36
	s_movk_i32 s17, 0xa0
	v_bitop3_b32 v180, v2, v4, s17 bitop3:0x36
	s_movk_i32 s17, 0xc0
	v_bitop3_b32 v181, v2, v4, s17 bitop3:0x36
	s_movk_i32 s17, 0xe0
	v_bitop3_b32 v182, v2, v4, s17 bitop3:0x36
	s_add_u32 s17, s52, 0x8000
	s_addc_u32 s18, s53, 0
	s_add_u32 s25, s48, 0x8000
	s_addc_u32 s28, s49, 0
	v_mov_b32_e32 v16, v3
	v_mov_b32_e32 v17, v3
	v_bitop3_b32 v176, v2, v4, 32 bitop3:0x36
	v_bitop3_b32 v177, v2, v4, 64 bitop3:0x36
	v_bitop3_b32 v179, v2, v4, s87 bitop3:0x36
	v_or_b32_e32 v183, 0x60e0, v2
	v_add_u32_e32 v184, 0, v2
	v_or_b32_e32 v185, 0x6000, v2
	s_add_u32 s48, s50, 0x200
	v_mov_b32_e32 v2, v3
	v_mov_b32_e32 v4, v3
	v_mov_b32_e32 v5, v3
	v_mov_b32_e32 v6, v3
	v_mov_b32_e32 v7, v3
	v_mov_b32_e32 v8, v3
	v_mov_b32_e32 v9, v3
	v_mov_b32_e32 v10, v3
	v_mov_b32_e32 v11, v3
	v_mov_b32_e32 v12, v3
	v_mov_b32_e32 v13, v3
	v_mov_b32_e32 v14, v3
	v_mov_b32_e32 v15, v3
	v_readlane_b32 s52, v255, 22
	v_mov_b64_e32 v[32:33], v[16:17]
	v_mov_b64_e32 v[48:49], v[16:17]
	v_mov_b64_e32 v[64:65], v[16:17]
	v_mov_b64_e32 v[80:81], v[16:17]
	s_mov_b32 s1, 2
	v_lshl_add_u32 v186, v173, 8, 0
	v_lshl_add_u32 v187, v173, 7, 0
	s_addc_u32 s49, s51, 0
	s_mov_b32 s36, 0
	v_mov_b32_e32 v162, 0
	s_mov_b64 s[50:51], 0
	v_readlane_b32 s53, v255, 23
	v_mov_b64_e32 v[30:31], v[14:15]
	v_mov_b64_e32 v[28:29], v[12:13]
	v_mov_b64_e32 v[26:27], v[10:11]
	v_mov_b64_e32 v[24:25], v[8:9]
	v_mov_b64_e32 v[22:23], v[6:7]
	v_mov_b64_e32 v[20:21], v[4:5]
	v_mov_b64_e32 v[18:19], v[2:3]
	v_mov_b64_e32 v[46:47], v[14:15]
	v_mov_b64_e32 v[44:45], v[12:13]
	v_mov_b64_e32 v[42:43], v[10:11]
	v_mov_b64_e32 v[40:41], v[8:9]
	v_mov_b64_e32 v[38:39], v[6:7]
	v_mov_b64_e32 v[36:37], v[4:5]
	v_mov_b64_e32 v[34:35], v[2:3]
	v_mov_b64_e32 v[62:63], v[14:15]
	v_mov_b64_e32 v[60:61], v[12:13]
	v_mov_b64_e32 v[58:59], v[10:11]
	v_mov_b64_e32 v[56:57], v[8:9]
	v_mov_b64_e32 v[54:55], v[6:7]
	v_mov_b64_e32 v[52:53], v[4:5]
	v_mov_b64_e32 v[50:51], v[2:3]
	s_mov_b32 s20, 0
	v_mov_b64_e32 v[78:79], v[14:15]
	v_mov_b64_e32 v[76:77], v[12:13]
	v_mov_b64_e32 v[74:75], v[10:11]
	v_mov_b64_e32 v[72:73], v[8:9]
	v_mov_b64_e32 v[70:71], v[6:7]
	v_mov_b64_e32 v[68:69], v[4:5]
	v_mov_b64_e32 v[66:67], v[2:3]
	v_readfirstlane_b32 s19, v0
	s_bitcmp1_b32 s19, 8
	s_cbranch_scc0 .Lpp_skip
	s_setprio 1
